# attention: next tile's first K fragment reads issued before the end-of-PV barrier (Y wait vmcnt(4), prologue vmcnt(4))
# baseline (speedup 1.0000x reference)
; template <int mode> ...
;   asm volatile("" : "+v"(tid));
;   const int wid = __builtin_amdgcn_readfirstlane(tid >> 6), lane = tid & 63, r32 = lane & 31, hi = lane >> 5;
;   const unsigned lds0 = (unsigned)(uintptr_t)lds;
;   float* ws = (float*)(lds + A_LDS_WS) + wid * 64; float* li_l = ws; float* al_l = ws + 32;
;   unsigned koff[2], voff[4];
; #pragma unroll
;   for (int i = 0; i < 2; ++i) { const int row = (wid * 2 + i) * 4 + (lane >> 4), chunk = (lane & 15) ^ (((row & 7) << 1) | ((row >> 3) & 1)); koff[i] = (unsigned)(row * (LDP * 2) + chunk * 16); }
; #pragma unroll
;   for (int i = 0; i < 4; ++i) { const int q = (wid & 3) * 4 + i, subtile = q * 2 + (lane >> 5), kk = (subtile >> 2) * 8 + ((lane & 31) >> 2);
;     const int k = (kk & ~0xC) | ((kk & 4) << 1) | ((kk & 8) >> 1), col = (subtile & 3) * 32 + (lane & 3) * 8;
;     voff[i] = (unsigned)(k * (LDP * 2) + ((wid >> 2) * 128 + col) * 2); }
;   const char* Kb = (const char*)Kh; const char* Vb = (const char*)Vh;
;   const unsigned kdst = lds0 + A_LDS_K + wid * 2048, vdst = lds0 + A_LDS_V + (wid >> 2) * 16384 + (wid & 3) * 4096;
;     ...
;   bf16x8 qr[8];
;   { const hbf* Qw = Qb + (long)(wid * QBLK + r32) * LDQ + hi * 8;
; #pragma unroll
;     for (int d0 = 0; d0 < 8; ++d0) qr[d0] = *reinterpret_cast<const bf16x8*>(Qw + d0 * 16); }
;   asm volatile("" : "+v"(qr[0]), "+v"(qr[1]), "+v"(qr[2]), "+v"(qr[3]), "+v"(qr[4]), "+v"(qr[5]), "+v"(qr[6]), "+v"(qr[7]));
;   DMA_K(0, 0); DMA_V(0, 0); DMA_K(1, 1); DMA_V(1, 1);
;   float m_reg = 0.f, l_reg = 0; f32x16 o[8] = {};
;   const int vb0 = (int)(lds0 + A_LDS_V) + v_rd_base(lane);
;   const int kb0 = (int)(lds0 + A_LDS_K) + r32 * 256, kc = (hi << 4) ^ ((((r32 & 7) << 1) | ((r32 >> 3) & 1)) << 4);
;   const int NT = seq / KVBLK;
;     ...
;   A_WAITBAR(6);
;   if (wid >= 4) asm volatile("s_barrier" ::: "memory");
; __global__ void __launch_bounds__(NWAVES * 64, 2) mega_fwd(Args args) {
;     ...
;                 const int h = set & 7, sq = set >> 3;
;                 const size_t krow = (size_t)sq * SEQ, qrow = krow + (size_t)qb * 256;
;                 const att::hbf* Vp = (const att::hbf*)(PROJ + krow * LDP + C_DV + h * 256);
;                 float* stash = OS + (size_t)bx * 65536;
;                 { const att::hbf* Qp = (const att::hbf*)(PROJ + qrow * LDP + C_DQ + (2 * h) * 128);
;                   const att::hbf* Kp = (const att::hbf*)(PROJ + krow * LDP + C_DK + (2 * h) * 128);
.LBB0_345:
	s_ashr_i32 s4, s10, 3
	s_ashr_i32 s5, s4, 31
	s_ashr_i32 s25, s24, 31
	s_lshl_b64 s[4:5], s[4:5], s72
	s_lshl_b64 s[6:7], s[24:25], 8
	s_add_u32 s46, s4, s6
	s_addc_u32 s47, s5, s7
	s_mul_i32 s0, s5, 0x6000
	s_mul_hi_u32 s5, s4, 0x6000
	s_add_i32 s11, s5, s0
	s_mul_i32 s38, s4, 0x6000
	s_add_u32 s0, s82, s38
	s_addc_u32 s6, s83, s11
	s_lshl_b32 s4, s10, 8
	s_and_b32 s4, s4, 0x700
	s_lshl_b32 s4, s4, 1
	s_add_u32 s9, s0, s4
	s_addc_u32 s12, s6, 0
	s_add_u32 s94, s9, 0x5000
	s_mul_i32 s5, s47, 0x6000
	s_mul_hi_u32 s7, s46, 0x6000
	s_addc_u32 s95, s12, 0
	s_add_i32 s7, s7, s5
	s_mul_i32 s5, s46, 0x6000
	s_add_u32 s5, s82, s5
	s_addc_u32 s7, s83, s7
	s_add_u32 s50, s5, 0x3000
	s_addc_u32 s51, s7, 0
	s_add_u32 s40, s50, s4
	s_addc_u32 s41, s51, 0
	s_add_u32 s5, s0, 0x4000
	s_addc_u32 s6, s6, 0
	v_mbcnt_lo_u32_b32 v0, -1, 0
	v_mbcnt_hi_u32_b32 v0, -1, v0
	s_add_u32 s24, s5, s4
	v_add_u32_e32 v1, s59, v0
	s_addc_u32 s25, s6, 0
	v_readfirstlane_b32 s8, v1
	s_ashr_i32 s28, s8, 6
	v_and_b32_e32 v0, 31, v1
	v_bfe_u32 v2, v1, 5, 1
	v_lshl_or_b32 v3, s28, 5, v0
	v_mov_b64_e32 v[4:5], s[40:41]
	v_mad_i64_i32 v[4:5], s[40:41], v3, s68, v[4:5]
	v_lshlrev_b32_e32 v198, 4, v2
	v_mov_b32_e32 v199, v193
	v_lshl_add_u64 v[4:5], v[4:5], 0, v[198:199]
	global_load_dwordx4 v[160:163], v[4:5], off offset:224
	global_load_dwordx4 v[164:167], v[4:5], off offset:192
	global_load_dwordx4 v[168:171], v[4:5], off offset:160
	global_load_dwordx4 v[172:175], v[4:5], off offset:128
	global_load_dwordx4 v[176:179], v[4:5], off offset:96
	global_load_dwordx4 v[180:183], v[4:5], off offset:64
	global_load_dwordx4 v[184:187], v[4:5], off offset:32
	global_load_dwordx4 v[188:191], v[4:5], off
	v_bfe_u32 v3, v1, 4, 2
	v_lshlrev_b32_e32 v7, 4, v1
	v_bfe_u32 v5, v1, 2, 3
	v_lshrrev_b32_e32 v6, 1, v1
	v_or_b32_e32 v9, 4, v3
	v_and_b32_e32 v7, 48, v7
	v_lshlrev_b32_e32 v10, 6, v2
	s_and_b32 s0, s8, 0xffffff00
	s_lshl_b32 s7, s8, 6
	s_lshl_b32 s13, s28, 3
	s_lshl_b32 s39, s28, 12
	v_and_b32_e32 v4, 15, v1
	v_lshlrev_b32_e32 v8, 1, v3
	v_and_b32_e32 v6, 8, v6
	v_lshlrev_b32_e32 v11, 1, v9
	s_and_b32 s29, s28, 1
	v_lshl_or_b32 v5, s28, 4, v5
	v_or3_b32 v7, s0, v7, v10
	s_lshl_b32 s0, s28, 11
	s_and_b32 s7, s7, 0xffffc000
	v_or_b32_e32 v3, s13, v3
	v_or_b32_e32 v9, s13, v9
	s_and_b32 s13, s39, 0x3000
	v_bitop3_b32 v8, v8, v4, s29 bitop3:0x36
	v_and_b32_e32 v5, 55, v5
	v_or_b32_e32 v6, 0x80, v7
	v_mul_lo_u32 v3, v3, s68
	v_mov_b32_e32 v10, 0x30000
	s_cmp_lg_u32 0, -1
	v_bitop3_b32 v4, v11, v4, s29 bitop3:0x36
	v_mul_lo_u32 v9, v9, s68
	v_mad_u32_u24 v204, v5, s68, v7
	v_mad_u32_u24 v206, v5, s68, v6
	v_mad_u32_u24 v5, v5, s68, v10
	v_lshl_or_b32 v192, v8, 4, v3
	s_cselect_b32 s29, 0, 0
	v_mov_b32_e32 v203, v193
	v_lshl_add_u32 v202, v4, 4, v9
	v_add_u32_e32 v208, v5, v7
	v_add_u32_e32 v210, v5, v6
	s_add_i32 s0, s0, s29
	s_add_i32 s7, s29, s7
	v_lshl_add_u64 v[6:7], s[24:25], 0, v[192:193]
	v_mov_b32_e32 v205, v193
	v_lshl_add_u64 v[8:9], s[24:25], 0, v[202:203]
	s_add_i32 s7, s7, s13
	s_add_i32 s13, s0, 0x400
	v_lshl_add_u64 v[4:5], s[94:95], 0, v[204:205]
	s_add_i32 s7, s7, 0xc000
	v_mov_b32_e32 v207, v193
	v_mov_b32_e32 v209, v193
	v_mov_b32_e32 v211, v193
	s_waitcnt vmcnt(0)
	s_mov_b32 s29, m0
	s_mov_b32 m0, s0
	s_nop 0
	global_load_lds_dwordx4 v[6:7], off
	s_mov_b32 m0, s29
	s_nop 0
	s_mov_b32 s29, m0
	s_mov_b32 m0, s13
	s_nop 0
	global_load_lds_dwordx4 v[8:9], off
	s_mov_b32 m0, s29
	s_mov_b32 s13, m0
	s_mov_b32 m0, s7
	s_nop 0
	global_load_lds_dwordx4 v[4:5], off
	s_mov_b32 m0, s13
	s_add_i32 s13, s7, 0x400
	v_lshl_add_u64 v[4:5], s[94:95], 0, v[206:207]
	s_mov_b32 s29, m0
	s_mov_b32 m0, s13
	s_nop 0
	global_load_lds_dwordx4 v[4:5], off
	s_mov_b32 m0, s29
	s_add_i32 s13, s7, 0x800
	v_lshl_add_u64 v[4:5], s[94:95], 0, v[208:209]
	s_mov_b32 s29, m0
	s_mov_b32 m0, s13
	s_nop 0
	global_load_lds_dwordx4 v[4:5], off
	s_mov_b32 m0, s29
	s_add_i32 s13, s7, 0xc00
	s_add_u32 s24, s24, 0x180000
	v_lshl_add_u64 v[4:5], s[94:95], 0, v[210:211]
	s_mov_b32 s29, m0
	s_mov_b32 m0, s13
	s_nop 0
	global_load_lds_dwordx4 v[4:5], off
	s_mov_b32 m0, s29
	s_addc_u32 s25, s25, 0
	s_add_i32 s13, s0, 0x4000
	v_lshl_add_u64 v[4:5], s[24:25], 0, v[192:193]
	s_mov_b32 s29, m0
	s_mov_b32 m0, s13
	s_nop 0
	global_load_lds_dwordx4 v[4:5], off
	s_mov_b32 m0, s29
	s_add_i32 s13, s0, 0x4400
	s_add_u32 s52, s9, 0x185000
	v_lshl_add_u64 v[4:5], s[24:25], 0, v[202:203]
	s_mov_b32 s24, m0
	s_mov_b32 m0, s13
	s_nop 0
	global_load_lds_dwordx4 v[4:5], off
	s_mov_b32 m0, s24
	s_addc_u32 s53, s12, 0
	s_add_i32 s9, s7, 0x8000
	v_lshl_add_u64 v[4:5], s[52:53], 0, v[204:205]
	s_mov_b32 s12, m0
	s_mov_b32 m0, s9
	s_nop 0
	global_load_lds_dwordx4 v[4:5], off
	s_mov_b32 m0, s12
	v_lshl_add_u64 v[4:5], s[52:53], 0, v[206:207]
	s_add_i32 s9, s7, 0x8400
	s_mov_b32 s12, m0
	s_mov_b32 m0, s9
	s_nop 0
	global_load_lds_dwordx4 v[4:5], off
	s_mov_b32 m0, s12
	v_lshl_add_u64 v[4:5], s[52:53], 0, v[208:209]
	s_add_i32 s9, s7, 0x8800
	s_mov_b32 s12, m0
	s_mov_b32 m0, s9
	s_nop 0
	global_load_lds_dwordx4 v[4:5], off
	s_mov_b32 m0, s12
	v_lshl_add_u64 v[4:5], s[52:53], 0, v[210:211]
	s_add_i32 s9, s7, 0x8c00
	s_mov_b32 s12, m0
	s_mov_b32 m0, s9
	s_nop 0
	global_load_lds_dwordx4 v[4:5], off
	s_mov_b32 m0, s12
	s_waitcnt vmcnt(4) lgkmcnt(0)
	s_barrier
	s_cmp_lt_i32 s28, 4
	s_cbranch_scc1 .LBB0_347
	s_barrier
; #define SBAR() __builtin_amdgcn_sched_barrier(0)
; __device__ __forceinline__ int v_rd_base(int lane) { return ((lane & 3) << 3) | (((lane >> 2) & 3) << 6) | (((lane >> 4) & 1) << 5) | (((lane >> 5) & 1) << 8); }
; #define KRD(A, B, d0) do { const int ad_ = (kc ^ ((d0) << 5)) + kbt; A = lds_rd128<0>(ad_); B = lds_rd128<8192>(ad_); } while (0)
; #define KW(N) do { asm volatile("s_waitcnt lgkmcnt(" #N ")" ::: "memory"); SBAR(); } while (0)
; #define A_WAITBAR(N) asm volatile("s_waitcnt vmcnt(" #N ") lgkmcnt(0) ; A256BAR\n\ts_barrier" ::: "memory")
; #define DMA_K(t, sl) do { const char* b_ = Kb + (size_t)(t) * TSTRIDE; const unsigned d_ = RFL(kdst + (sl) * 16384); glds16(b_ + koff[0], d_); glds16(b_ + koff[1], d_ + 1024); } while (0)
; __device__ __forceinline__ void qkt_pipe(f32x16& p0, f32x16& p1, int kbt, int kc, const bf16x8* qr, const f32x16& z) {
;   bf16x8 a0, b0, a1, b1, a2, b2, a3, b3;
;     ...
;   KRD(a0, b0, 0); KRD(a1, b1, 1); KRD(a2, b2, 2); KRD(a3, b3, 3);
;   KW(6); p0 = __builtin_amdgcn_mfma_f32_32x32x16_bf16(a0, qr[0], z, 0, 0, 0);  p1 = __builtin_amdgcn_mfma_f32_32x32x16_bf16(b0, qr[0], z, 0, 0, 0);  SBAR(); KRD(a0, b0, 4);
; template <int mode> ...
;     ...
;   float m_reg = 0.f, l_reg = 0; f32x16 o[8] = {};
;   const int vb0 = (int)(lds0 + A_LDS_V) + v_rd_base(lane);
;   const int kb0 = (int)(lds0 + A_LDS_K) + r32 * 256, kc = (hi << 4) ^ ((((r32 & 7) << 1) | ((r32 >> 3) & 1)) << 4);
;   const int NT = seq / KVBLK;
;     ...
;   A_WAITBAR(6);
;   if (wid >= 4) asm volatile("s_barrier" ::: "memory");
;   int s0 = 0, s1 = 1, s2 = 2;
;   for (int j = 0; j < NT; ++j) {
;     const bool more = j + 2 < NT;
;     if (more) DMA_K(j + 2, s2);
;     f32x16 p0, p1; bf16x8 pa0, pa1, pa2, pa3;
;     __builtin_amdgcn_s_setprio(2);
;     { f32x16 negm;
; #pragma unroll
;       for (int r = 0; r < 16; ++r) negm[r] = -m_reg;
;       qkt_pipe(p0, p1, kb0 + s0 * 16384, kc, qr, negm); }
.LBB0_347:
	s_and_b32 s8, s8, 0x3fffffc0
	s_lshl_b32 s8, s8, 2
	s_add_i32 s8, s8, 0
	s_add_i32 s8, s8, 0x24000
	s_cmp_lg_u32 0, -1
	s_cselect_b32 s12, 0, 0
	v_lshlrev_b32_e32 v7, 1, v1
	s_and_b32 s10, s10, 7
	v_and_b32_e32 v3, 63, v1
	v_lshl_add_u32 v199, v0, 8, s12
	v_and_b32_e32 v7, 14, v7
	v_bfe_u32 v1, v1, 3, 1
	s_add_i32 s12, s12, 0xc000
	s_lshl_b32 s10, s10, 9
	v_lshlrev_b32_e32 v4, 3, v3
	v_bitop3_b32 v1, v7, v2, v1 bitop3:0x36
	s_add_u32 s10, s38, s10
	v_lshlrev_b32_e32 v200, 4, v3
	v_lshlrev_b32_e32 v6, 1, v3
	v_lshlrev_b32_e32 v213, 4, v1
	v_and_b32_e32 v1, 0x118, v4
	s_addc_u32 s11, s11, 0
	v_and_b32_e32 v5, 0xc0, v200
	v_lshl_add_u32 v201, v0, 2, s8
	v_and_or_b32 v0, v6, 32, v1
	s_add_u32 s60, s14, s10
	v_readlane_b32 s10, v254, 60
	v_mov_b32_e32 v112, v193
	v_mov_b32_e32 v113, v193
	v_cmp_gt_u32_e64 s[40:41], 32, v3
	v_add3_u32 v223, v5, s12, v0
	s_addc_u32 s61, s10, s11
	v_mov_b32_e32 v114, v193
	v_mov_b32_e32 v115, v193
	v_mov_b32_e32 v116, v193
	v_mov_b32_e32 v117, v193
	v_mov_b32_e32 v118, v193
	v_mov_b32_e32 v119, v193
	v_mov_b32_e32 v120, v193
	v_mov_b32_e32 v121, v193
	v_mov_b32_e32 v122, v193
	v_mov_b32_e32 v123, v193
	v_mov_b32_e32 v124, v193
	v_mov_b32_e32 v125, v193
	v_mov_b32_e32 v126, v193
	v_mov_b32_e32 v127, v193
	v_mov_b64_e32 v[96:97], v[112:113]
	v_mov_b64_e32 v[80:81], v[112:113]
	v_mov_b64_e32 v[64:65], v[112:113]
	v_mov_b64_e32 v[48:49], v[112:113]
	v_mov_b64_e32 v[32:33], v[112:113]
	v_mov_b64_e32 v[16:17], v[112:113]
	v_mov_b64_e32 v[0:1], v[112:113]
	s_mov_b32 s9, 2
	s_mov_b32 s29, 1
	s_mov_b32 s24, 0
	v_mov_b32_e32 v224, 0
	s_mov_b64 s[38:39], s[60:61]
	v_mov_b64_e32 v[98:99], v[114:115]
	v_mov_b64_e32 v[100:101], v[116:117]
	v_mov_b64_e32 v[102:103], v[118:119]
	v_mov_b64_e32 v[104:105], v[120:121]
	v_mov_b64_e32 v[106:107], v[122:123]
	v_mov_b64_e32 v[108:109], v[124:125]
	v_mov_b64_e32 v[110:111], v[126:127]
	v_mov_b64_e32 v[82:83], v[114:115]
	v_mov_b64_e32 v[84:85], v[116:117]
	v_mov_b64_e32 v[86:87], v[118:119]
	v_mov_b64_e32 v[88:89], v[120:121]
	v_mov_b64_e32 v[90:91], v[122:123]
	v_mov_b64_e32 v[92:93], v[124:125]
	v_mov_b64_e32 v[94:95], v[126:127]
	v_mov_b64_e32 v[66:67], v[114:115]
	v_mov_b64_e32 v[68:69], v[116:117]
	v_mov_b64_e32 v[70:71], v[118:119]
	v_mov_b64_e32 v[72:73], v[120:121]
	v_mov_b64_e32 v[74:75], v[122:123]
	v_mov_b64_e32 v[76:77], v[124:125]
	v_mov_b64_e32 v[78:79], v[126:127]
	v_mov_b64_e32 v[50:51], v[114:115]
	v_mov_b64_e32 v[52:53], v[116:117]
	v_mov_b64_e32 v[54:55], v[118:119]
	v_mov_b64_e32 v[56:57], v[120:121]
	v_mov_b64_e32 v[58:59], v[122:123]
	v_mov_b64_e32 v[60:61], v[124:125]
	v_mov_b64_e32 v[62:63], v[126:127]
	v_mov_b64_e32 v[34:35], v[114:115]
	v_mov_b64_e32 v[36:37], v[116:117]
	v_mov_b64_e32 v[38:39], v[118:119]
	v_mov_b64_e32 v[40:41], v[120:121]
	v_mov_b64_e32 v[42:43], v[122:123]
	v_mov_b64_e32 v[44:45], v[124:125]
	v_mov_b64_e32 v[46:47], v[126:127]
	v_mov_b64_e32 v[18:19], v[114:115]
	v_mov_b64_e32 v[20:21], v[116:117]
	v_mov_b64_e32 v[22:23], v[118:119]
	v_mov_b64_e32 v[24:25], v[120:121]
	v_mov_b64_e32 v[26:27], v[122:123]
	v_mov_b64_e32 v[28:29], v[124:125]
	v_mov_b64_e32 v[30:31], v[126:127]
	v_mov_b64_e32 v[2:3], v[114:115]
	v_mov_b64_e32 v[4:5], v[116:117]
	v_mov_b64_e32 v[6:7], v[118:119]
	v_mov_b64_e32 v[8:9], v[120:121]
	v_mov_b64_e32 v[10:11], v[122:123]
	v_mov_b64_e32 v[12:13], v[124:125]
	v_mov_b64_e32 v[14:15], v[126:127]
	s_mov_b32 s10, 0
	v_mov_b32_e32 v225, 0
	v_lshl_add_u32 v212, s24, 14, v199
	v_add_u32_e32 v144, v212, v213
	ds_read_b128 v[194:197], v144 offset:0
	ds_read_b128 v[226:229], v144 offset:0x2000
	v_xor_b32_e32 v144, 32, v213
	v_add_u32_e32 v144, v212, v144
	ds_read_b128 v[230:233], v144 offset:0
	ds_read_b128 v[234:237], v144 offset:0x2000
	v_xor_b32_e32 v144, 64, v213
	v_add_u32_e32 v144, v212, v144
	ds_read_b128 v[238:241], v144 offset:0
	ds_read_b128 v[242:245], v144 offset:0x2000
	v_xor_b32_e32 v144, 0x60, v213
	v_add_u32_e32 v144, v212, v144
	ds_read_b128 v[246:249], v144 offset:0
	ds_read_b128 v[214:217], v144 offset:0x2000
.LBB0_348:
	s_mov_b32 s11, s24
	s_setprio 2
	s_add_i32 s12, s10, 2
	s_cmp_lt_u32 s12, s74
	s_cselect_b64 s[56:57], -1, 0
	s_cmp_ge_u32 s12, s74
	s_cselect_b64 s[90:91], -1, 0
	s_and_b64 vcc, exec, s[90:91]
	v_xor_b32_e32 v128, 0x80000000, v224
	v_mov_b32_e32 v129, v128
	v_mov_b32_e32 v130, v128
	v_mov_b32_e32 v131, v128
	v_mov_b32_e32 v132, v128
	v_mov_b32_e32 v133, v128
	v_mov_b32_e32 v134, v128
	v_mov_b32_e32 v135, v128
	v_mov_b32_e32 v136, v128
	v_mov_b32_e32 v137, v128
	v_mov_b32_e32 v138, v128
	v_mov_b32_e32 v139, v128
	v_mov_b32_e32 v140, v128
	v_mov_b32_e32 v141, v128
	v_mov_b32_e32 v142, v128
	v_mov_b32_e32 v143, v128
	s_waitcnt lgkmcnt(6)
	s_nop 1
	v_mfma_f32_32x32x16_bf16 v[144:159], v[194:197], v[188:191], v[128:143]
	v_mfma_f32_32x32x16_bf16 v[128:143], v[226:229], v[188:191], v[128:143]
	v_xor_b32_e32 v194, 0x80, v213
	v_add_u32_e32 v220, v212, v194
	ds_read_b128 v[194:197], v220 offset:0
	ds_read_b128 v[226:229], v220 offset:0x2000
	s_cbranch_vccnz .Lq0_nodma
	s_add_u32 s24, s38, 0xfffff000
	s_addc_u32 s25, s39, -1
	s_lshl_b32 s12, s9, 14
	s_add_i32 s12, s12, s0
	s_mov_b32 s13, m0
	s_mov_b32 m0, s12
	s_nop 0
	global_load_lds_dwordx4 v192, s[24:25]
	s_addk_i32 s12, 0x400
	s_mov_b32 m0, s12
	s_nop 0
	global_load_lds_dwordx4 v202, s[24:25]
	s_mov_b32 m0, s13

; #define SBAR() __builtin_amdgcn_sched_barrier(0)
; #define VF_WAIT(N) do { asm volatile("s_waitcnt lgkmcnt(" #N ")" ::: "memory"); SBAR(); } while (0)
; #define A_WAITBAR(N) asm volatile("s_waitcnt vmcnt(" #N ") lgkmcnt(0) ; A256BAR\n\ts_barrier" ::: "memory")
; __device__ __forceinline__ float softmax_rel(f32x16& p0, f32x16& p1, bool first, float& m_reg, float& l_reg, bf16x8& pa0, bf16x8& pa1, bf16x8& pa2, bf16x8& pa3) {
;     ...
;     ps = __uint_as_float(rr[0]) + __uint_as_float(rr[1]); }
;   l_reg = l_reg * alpha + ps;
; __device__ __forceinline__ void pv8(f32x16* o, int vb, bf16x8 pa0, bf16x8 pa1, bf16x8 pa2, bf16x8 pa3) {
;   VFrag fa, fb; const int vb2 = vb + 16384;
;   vf_read<0>(fa, vb);
;   vf_read<1>(fb, vb);  VF_WAIT(8); vf_mma(o[0], fa, pa0, pa1, pa2, pa3); SBAR();
;   vf_read<2>(fa, vb);  VF_WAIT(8); vf_mma(o[1], fb, pa0, pa1, pa2, pa3); SBAR();
;   vf_read<3>(fb, vb);  VF_WAIT(8); vf_mma(o[2], fa, pa0, pa1, pa2, pa3); SBAR();
;   vf_read<0>(fa, vb2); VF_WAIT(8); vf_mma(o[3], fb, pa0, pa1, pa2, pa3); SBAR();
;   vf_read<1>(fb, vb2); VF_WAIT(8); vf_mma(o[4], fa, pa0, pa1, pa2, pa3); SBAR();
;   vf_read<2>(fa, vb2); VF_WAIT(8); vf_mma(o[5], fb, pa0, pa1, pa2, pa3); SBAR();
;   vf_read<3>(fb, vb2); VF_WAIT(8); vf_mma(o[6], fa, pa0, pa1, pa2, pa3); SBAR();
;   VF_WAIT(0); vf_mma(o[7], fb, pa0, pa1, pa2, pa3);
; }
; template <int mode> ...
;     ...
;     if (more) A_WAITBAR(6); else A_WAITBAR(0);
;     { const int t_ = s0; s0 = s1; s1 = s2; s2 = t_; }
.Lp0_nodma:
	s_waitcnt lgkmcnt(8)
	v_mfma_f32_32x32x16_bf16 v[96:111], v[128:131], v[194:197], v[96:111]
	v_mfma_f32_32x32x16_bf16 v[96:111], v[132:135], v[214:217], v[96:111]
	v_mfma_f32_32x32x16_bf16 v[96:111], v[136:139], v[228:231], v[96:111]
	v_mfma_f32_32x32x16_bf16 v[96:111], v[140:143], v[232:235], v[96:111]
	ds_read_b64_tr_b16 v[194:195], v220 offset:0x600
	ds_read_b64_tr_b16 v[196:197], v220 offset:0xe00
	ds_read_b64_tr_b16 v[214:215], v220 offset:0x1600
	ds_read_b64_tr_b16 v[216:217], v220 offset:0x1e00
	ds_read_b64_tr_b16 v[228:229], v220 offset:0x2600
	ds_read_b64_tr_b16 v[230:231], v220 offset:0x2e00
	ds_read_b64_tr_b16 v[232:233], v220 offset:0x3600
	ds_read_b64_tr_b16 v[234:235], v220 offset:0x3e00
	s_waitcnt lgkmcnt(8)
	v_mfma_f32_32x32x16_bf16 v[80:95], v[128:131], v[144:147], v[80:95]
	v_mfma_f32_32x32x16_bf16 v[80:95], v[132:135], v[148:151], v[80:95]
	v_mfma_f32_32x32x16_bf16 v[80:95], v[136:139], v[152:155], v[80:95]
	v_mfma_f32_32x32x16_bf16 v[80:95], v[140:143], v[156:159], v[80:95]
	ds_read_b64_tr_b16 v[144:145], v221 offset:0
	ds_read_b64_tr_b16 v[146:147], v221 offset:0x800
	ds_read_b64_tr_b16 v[148:149], v221 offset:0x1000
	ds_read_b64_tr_b16 v[150:151], v221 offset:0x1800
	ds_read_b64_tr_b16 v[152:153], v221 offset:0x2000
	ds_read_b64_tr_b16 v[154:155], v221 offset:0x2800
	ds_read_b64_tr_b16 v[156:157], v221 offset:0x3000
	ds_read_b64_tr_b16 v[158:159], v221 offset:0x3800
	s_waitcnt lgkmcnt(8)
	v_mfma_f32_32x32x16_bf16 v[64:79], v[128:131], v[194:197], v[64:79]
	v_mfma_f32_32x32x16_bf16 v[64:79], v[132:135], v[214:217], v[64:79]
	v_mfma_f32_32x32x16_bf16 v[64:79], v[136:139], v[228:231], v[64:79]
	v_mfma_f32_32x32x16_bf16 v[64:79], v[140:143], v[232:235], v[64:79]
	ds_read_b64_tr_b16 v[194:195], v221 offset:0x200
	ds_read_b64_tr_b16 v[196:197], v221 offset:0xa00
	ds_read_b64_tr_b16 v[214:215], v221 offset:0x1200
	ds_read_b64_tr_b16 v[216:217], v221 offset:0x1a00
	ds_read_b64_tr_b16 v[228:229], v221 offset:0x2200
	ds_read_b64_tr_b16 v[230:231], v221 offset:0x2a00
	ds_read_b64_tr_b16 v[232:233], v221 offset:0x3200
	ds_read_b64_tr_b16 v[234:235], v221 offset:0x3a00
	s_waitcnt lgkmcnt(8)
	v_mfma_f32_32x32x16_bf16 v[48:63], v[128:131], v[144:147], v[48:63]
	v_mfma_f32_32x32x16_bf16 v[48:63], v[132:135], v[148:151], v[48:63]
	v_mfma_f32_32x32x16_bf16 v[48:63], v[136:139], v[152:155], v[48:63]
	v_mfma_f32_32x32x16_bf16 v[48:63], v[140:143], v[156:159], v[48:63]
	ds_read_b64_tr_b16 v[144:145], v221 offset:0x400
	ds_read_b64_tr_b16 v[146:147], v221 offset:0xc00
	ds_read_b64_tr_b16 v[148:149], v221 offset:0x1400
	ds_read_b64_tr_b16 v[150:151], v221 offset:0x1c00
	ds_read_b64_tr_b16 v[152:153], v221 offset:0x2400
	ds_read_b64_tr_b16 v[154:155], v221 offset:0x2c00
	ds_read_b64_tr_b16 v[156:157], v221 offset:0x3400
	ds_read_b64_tr_b16 v[158:159], v221 offset:0x3c00
	s_waitcnt lgkmcnt(8)
	v_mfma_f32_32x32x16_bf16 v[32:47], v[128:131], v[194:197], v[32:47]
	v_mfma_f32_32x32x16_bf16 v[32:47], v[132:135], v[214:217], v[32:47]
	v_mfma_f32_32x32x16_bf16 v[32:47], v[136:139], v[228:231], v[32:47]
	v_mfma_f32_32x32x16_bf16 v[32:47], v[140:143], v[232:235], v[32:47]
	ds_read_b64_tr_b16 v[194:195], v221 offset:0x600
	ds_read_b64_tr_b16 v[196:197], v221 offset:0xe00
	ds_read_b64_tr_b16 v[214:215], v221 offset:0x1600
	ds_read_b64_tr_b16 v[216:217], v221 offset:0x1e00
	ds_read_b64_tr_b16 v[228:229], v221 offset:0x2600
	ds_read_b64_tr_b16 v[230:231], v221 offset:0x2e00
	ds_read_b64_tr_b16 v[232:233], v221 offset:0x3600
	ds_read_b64_tr_b16 v[234:235], v221 offset:0x3e00
	s_waitcnt lgkmcnt(8)
	v_mfma_f32_32x32x16_bf16 v[16:31], v[128:131], v[144:147], v[16:31]
	v_mfma_f32_32x32x16_bf16 v[16:31], v[132:135], v[148:151], v[16:31]
	v_mfma_f32_32x32x16_bf16 v[16:31], v[136:139], v[152:155], v[16:31]
	v_mfma_f32_32x32x16_bf16 v[16:31], v[140:143], v[156:159], v[16:31]
	s_waitcnt lgkmcnt(0)
	v_mfma_f32_32x32x16_bf16 v[0:15], v[128:131], v[194:197], v[0:15]
	s_and_b64 vcc, exec, s[90:91]
	v_mfma_f32_32x32x16_bf16 v[0:15], v[132:135], v[214:217], v[0:15]
	v_mfma_f32_32x32x16_bf16 v[0:15], v[136:139], v[228:231], v[0:15]
	v_mfma_f32_32x32x16_bf16 v[0:15], v[140:143], v[232:235], v[0:15]
	v_add_f32_e32 v128, v212, v227
	v_fmac_f32_e32 v128, v225, v226
	s_add_i32 s12, s10, 1
	s_cmp_ge_u32 s12, s74
	s_cbranch_scc1 .Lm0_nopre
	v_lshl_add_u32 v212, s29, 14, v199
	v_add_u32_e32 v144, v212, v213
	ds_read_b128 v[194:197], v144 offset:0
	ds_read_b128 v[226:229], v144 offset:0x2000
	v_xor_b32_e32 v144, 32, v213
	v_add_u32_e32 v144, v212, v144
	ds_read_b128 v[230:233], v144 offset:0
	ds_read_b128 v[234:237], v144 offset:0x2000
	v_xor_b32_e32 v144, 64, v213
	v_add_u32_e32 v144, v212, v144
	ds_read_b128 v[238:241], v144 offset:0
	ds_read_b128 v[242:245], v144 offset:0x2000
	v_xor_b32_e32 v144, 0x60, v213
	v_add_u32_e32 v144, v212, v144
	ds_read_b128 v[246:249], v144 offset:0
	ds_read_b128 v[214:217], v144 offset:0x2000
.Lm0_nopre:
	s_cbranch_vccnz .Lm0_ybar0
	s_waitcnt vmcnt(4)
	s_barrier
.LBB0_367:
	s_add_i32 s10, s10, 1
	s_add_u32 s38, s38, 0x180000
	s_addc_u32 s39, s39, 0
	s_cmp_eq_u32 s74, s10
	s_cbranch_scc1 .LBB0_374
	s_mov_b32 s24, s29
	s_mov_b32 s29, s9
	s_mov_b32 s9, s11
	v_mov_b32_e32 v225, v128
	s_branch .LBB0_348

; #define A_WAITBAR(N) asm volatile("s_waitcnt vmcnt(" #N ") lgkmcnt(0) ; A256BAR\n\ts_barrier" ::: "memory")
; template <int mode> ...
;     ...
;     if (more) A_WAITBAR(6); else A_WAITBAR(0);
.Lm0_ybar0:
	s_waitcnt vmcnt(0)
	s_barrier
	s_branch .LBB0_367

; __device__ __forceinline__ int crow(int r, int hi) { return (r & 3) + 8 * (r >> 2) + 4 * hi; }
; template <int mode> ...
;     ...
;   if (wid < 4) asm volatile("s_barrier" ::: "memory");
;   if (hi == 0) li_l[r32] = l_reg; asm volatile("s_waitcnt lgkmcnt(0)" ::: "memory");
;   float rli[16];
; #pragma unroll
;   for (int r = 0; r < 16; ++r) rli[r] = __builtin_amdgcn_rcpf(li_l[crow(r, hi)]);
;   typedef float f32x4_t __attribute__((ext_vector_type(4)));
;   f32x4_t* st4 = (f32x4_t*)stash + (size_t)wid * 2048 + lane;
;   if constexpr (mode == 0) {
; #pragma unroll
;     for (int d0 = 0; d0 < 8; ++d0)
; #pragma unroll
;       for (int q = 0; q < 4; ++q) st4[(d0 * 4 + q) * 64] = (f32x4_t){o[d0][4 * q] * rli[4 * q], o[d0][4 * q + 1] * rli[4 * q + 1], o[d0][4 * q + 2] * rli[4 * q + 2], o[d0][4 * q + 3] * rli[4 * q + 3]};
.LBB0_376:
	s_and_saveexec_b64 s[24:25], s[40:41]
	ds_write_b32 v201, v128
	s_or_b64 exec, exec, s[24:25]
	s_waitcnt lgkmcnt(0)
	v_add_u32_e32 v136, s8, v198
	ds_read_b128 v[128:131], v136
	ds_read_b128 v[132:135], v136 offset:32
	s_ashr_i32 s29, s28, 31
	s_lshl_b64 s[8:9], s[28:29], 15
	ds_read_b128 v[144:147], v136 offset:96
	s_waitcnt lgkmcnt(2)
	v_rcp_f32_e32 v142, v128
	v_rcp_f32_e32 v143, v129
	v_rcp_f32_e32 v140, v130
	v_rcp_f32_e32 v141, v131
	ds_read_b128 v[128:131], v136 offset:64
	s_waitcnt lgkmcnt(2)
	v_rcp_f32_e32 v132, v132
	v_rcp_f32_e32 v133, v133
	v_rcp_f32_e32 v138, v134
	v_rcp_f32_e32 v139, v135
	s_waitcnt lgkmcnt(0)
	v_rcp_f32_e32 v136, v128
	v_rcp_f32_e32 v137, v129
	v_rcp_f32_e32 v134, v130
	v_rcp_f32_e32 v135, v131
	v_readlane_b32 s0, v253, 46
	v_rcp_f32_e32 v130, v144
	v_rcp_f32_e32 v131, v145
	v_rcp_f32_e32 v128, v146
	v_rcp_f32_e32 v129, v147
	s_add_u32 s8, s0, s8
	v_readlane_b32 s0, v253, 47
	s_addc_u32 s9, s0, s9
	v_pk_mul_f32 v[112:113], v[112:113], v[142:143]
	v_pk_mul_f32 v[114:115], v[114:115], v[140:141]
	global_store_dwordx4 v200, v[112:115], s[8:9]
	v_mov_b32_e32 v201, v193
	v_lshl_add_u64 v[144:145], s[8:9], 0, v[200:201]
	v_pk_mul_f32 v[112:113], v[116:117], v[132:133]
	v_pk_mul_f32 v[114:115], v[118:119], v[138:139]
	global_store_dwordx4 v200, v[112:115], s[8:9] offset:1024
	s_movk_i32 s0, 0x1000
	v_pk_mul_f32 v[80:81], v[80:81], v[142:143]
	v_pk_mul_f32 v[112:113], v[120:121], v[136:137]
	v_pk_mul_f32 v[114:115], v[122:123], v[134:135]
	global_store_dwordx4 v200, v[112:115], s[8:9] offset:2048
	v_pk_mul_f32 v[82:83], v[82:83], v[140:141]
	v_pk_mul_f32 v[48:49], v[48:49], v[142:143]
	v_pk_mul_f32 v[112:113], v[124:125], v[130:131]
	v_pk_mul_f32 v[114:115], v[126:127], v[128:129]
	global_store_dwordx4 v200, v[112:115], s[8:9] offset:3072
	v_pk_mul_f32 v[50:51], v[50:51], v[140:141]
	v_pk_mul_f32 v[16:17], v[16:17], v[142:143]
	v_add_co_u32_e32 v112, vcc, s0, v144
	s_movk_i32 s0, 0x3000
	s_nop 0
	v_addc_co_u32_e32 v113, vcc, 0, v145, vcc
	v_add_co_u32_e32 v114, vcc, s15, v144
	v_pk_mul_f32 v[18:19], v[18:19], v[140:141]
	s_nop 0
	v_addc_co_u32_e32 v115, vcc, 0, v145, vcc
	global_store_dwordx4 v[114:115], v[80:83], off
	v_pk_mul_f32 v[96:97], v[96:97], v[142:143]
	v_pk_mul_f32 v[98:99], v[98:99], v[140:141]
	v_pk_mul_f32 v[80:81], v[84:85], v[132:133]
	v_pk_mul_f32 v[82:83], v[86:87], v[138:139]
	global_store_dwordx4 v[114:115], v[80:83], off offset:1024
	v_pk_mul_f32 v[64:65], v[64:65], v[142:143]
	v_pk_mul_f32 v[66:67], v[66:67], v[140:141]
	v_pk_mul_f32 v[80:81], v[88:89], v[136:137]
	v_pk_mul_f32 v[82:83], v[90:91], v[134:135]
	global_store_dwordx4 v[114:115], v[80:83], off offset:2048
	v_pk_mul_f32 v[32:33], v[32:33], v[142:143]
	v_pk_mul_f32 v[34:35], v[34:35], v[140:141]
	v_pk_mul_f32 v[80:81], v[92:93], v[130:131]
	v_pk_mul_f32 v[82:83], v[94:95], v[128:129]
	global_store_dwordx4 v[114:115], v[80:83], off offset:3072
	v_pk_mul_f32 v[0:1], v[0:1], v[142:143]
	v_pk_mul_f32 v[2:3], v[2:3], v[140:141]
	v_add_co_u32_e32 v80, vcc, s0, v144
	s_movk_i32 s0, 0x4000
	s_nop 0
	v_addc_co_u32_e32 v81, vcc, 0, v145, vcc
	v_add_co_u32_e32 v82, vcc, s0, v144
	s_movk_i32 s0, 0x5000
	s_nop 0
	v_addc_co_u32_e32 v83, vcc, 0, v145, vcc
	global_store_dwordx4 v[82:83], v[48:51], off
	global_store_dwordx4 v[114:115], v[96:99], off offset:-4096
	global_store_dwordx4 v[82:83], v[64:67], off offset:-4096
	v_pk_mul_f32 v[48:49], v[52:53], v[132:133]
	v_pk_mul_f32 v[50:51], v[54:55], v[138:139]
	global_store_dwordx4 v[82:83], v[48:51], off offset:1024
	v_pk_mul_f32 v[96:97], v[100:101], v[132:133]
	v_pk_mul_f32 v[98:99], v[102:103], v[138:139]
	v_pk_mul_f32 v[48:49], v[56:57], v[136:137]
	v_pk_mul_f32 v[50:51], v[58:59], v[134:135]
	global_store_dwordx4 v[82:83], v[48:51], off offset:2048
	v_pk_mul_f32 v[64:65], v[68:69], v[132:133]
	v_pk_mul_f32 v[66:67], v[70:71], v[138:139]
	v_pk_mul_f32 v[48:49], v[60:61], v[130:131]
	v_pk_mul_f32 v[50:51], v[62:63], v[128:129]
	global_store_dwordx4 v[82:83], v[48:51], off offset:3072
	global_store_dwordx4 v[112:113], v[96:99], off offset:1024
	global_store_dwordx4 v[80:81], v[64:67], off offset:1024
	v_add_co_u32_e32 v48, vcc, s0, v144
	s_movk_i32 s0, 0x7000
	s_nop 0
	v_addc_co_u32_e32 v49, vcc, 0, v145, vcc
	v_add_co_u32_e32 v50, vcc, s68, v144
	v_pk_mul_f32 v[96:97], v[104:105], v[136:137]
	s_nop 0
	v_addc_co_u32_e32 v51, vcc, 0, v145, vcc
	global_store_dwordx4 v[50:51], v[16:19], off
	global_store_dwordx4 v[50:51], v[32:35], off offset:-4096
	v_pk_mul_f32 v[98:99], v[106:107], v[134:135]
	v_pk_mul_f32 v[16:17], v[20:21], v[132:133]
	v_pk_mul_f32 v[18:19], v[22:23], v[138:139]
	global_store_dwordx4 v[50:51], v[16:19], off offset:1024
	v_pk_mul_f32 v[32:33], v[36:37], v[132:133]
	v_pk_mul_f32 v[34:35], v[38:39], v[138:139]
	v_pk_mul_f32 v[16:17], v[24:25], v[136:137]
	v_pk_mul_f32 v[18:19], v[26:27], v[134:135]
	global_store_dwordx4 v[50:51], v[16:19], off offset:2048
	v_pk_mul_f32 v[64:65], v[72:73], v[136:137]
	v_pk_mul_f32 v[66:67], v[74:75], v[134:135]
	v_pk_mul_f32 v[16:17], v[28:29], v[130:131]
	v_pk_mul_f32 v[18:19], v[30:31], v[128:129]
	global_store_dwordx4 v[50:51], v[16:19], off offset:3072
	global_store_dwordx4 v[48:49], v[32:35], off offset:1024
	global_store_dwordx4 v[112:113], v[96:99], off offset:2048
	v_add_co_u32_e32 v16, vcc, s0, v144
	v_pk_mul_f32 v[32:33], v[40:41], v[136:137]
	s_nop 0
	v_addc_co_u32_e32 v17, vcc, 0, v145, vcc
	global_store_dwordx4 v[16:17], v[0:3], off
	v_pk_mul_f32 v[34:35], v[42:43], v[134:135]
	v_pk_mul_f32 v[96:97], v[108:109], v[130:131]
	v_pk_mul_f32 v[0:1], v[4:5], v[132:133]
	v_pk_mul_f32 v[2:3], v[6:7], v[138:139]
; __device__ __forceinline__ int v_rd_base(int lane) { return ((lane & 3) << 3) | (((lane >> 2) & 3) << 6) | (((lane >> 4) & 1) << 5) | (((lane >> 5) & 1) << 8); }
; #define CUR_TID() (wave_s * 64 + LANE_ID())
; template <int mode> ...
;   asm volatile("" : "+v"(tid));
;   const int wid = __builtin_amdgcn_readfirstlane(tid >> 6), lane = tid & 63, r32 = lane & 31, hi = lane >> 5;
;   const unsigned lds0 = (unsigned)(uintptr_t)lds;
;   float* ws = (float*)(lds + A_LDS_WS) + wid * 64; float* li_l = ws; float* al_l = ws + 32;
;   unsigned koff[2], voff[4];
; #pragma unroll
;   for (int i = 0; i < 2; ++i) { const int row = (wid * 2 + i) * 4 + (lane >> 4), chunk = (lane & 15) ^ (((row & 7) << 1) | ((row >> 3) & 1)); koff[i] = (unsigned)(row * (LDP * 2) + chunk * 16); }
; #pragma unroll
;   for (int i = 0; i < 4; ++i) { const int q = (wid & 3) * 4 + i, subtile = q * 2 + (lane >> 5), kk = (subtile >> 2) * 8 + ((lane & 31) >> 2);
;     const int k = (kk & ~0xC) | ((kk & 4) << 1) | ((kk & 8) >> 1), col = (subtile & 3) * 32 + (lane & 3) * 8;
;     voff[i] = (unsigned)(k * (LDP * 2) + ((wid >> 2) * 128 + col) * 2); }
;   const char* Kb = (const char*)Kh; const char* Vb = (const char*)Vh;
;   const unsigned kdst = lds0 + A_LDS_K + wid * 2048, vdst = lds0 + A_LDS_V + (wid >> 2) * 16384 + (wid & 3) * 4096;
;     ...
;   bf16x8 qr[8];
;   { const hbf* Qw = Qb + (long)(wid * QBLK + r32) * LDQ + hi * 8;
; #pragma unroll
;     for (int d0 = 0; d0 < 8; ++d0) qr[d0] = *reinterpret_cast<const bf16x8*>(Qw + d0 * 16); }
;   asm volatile("" : "+v"(qr[0]), "+v"(qr[1]), "+v"(qr[2]), "+v"(qr[3]), "+v"(qr[4]), "+v"(qr[5]), "+v"(qr[6]), "+v"(qr[7]));
;   DMA_K(0, 0); DMA_V(0, 0); DMA_K(1, 1); DMA_V(1, 1);
;   float m_reg = 0.f, l_reg = 0; f32x16 o[8] = {};
;   const int vb0 = (int)(lds0 + A_LDS_V) + v_rd_base(lane);
;   const int kb0 = (int)(lds0 + A_LDS_K) + r32 * 256, kc = (hi << 4) ^ ((((r32 & 7) << 1) | ((r32 >> 3) & 1)) << 4);
;   const int NT = seq / KVBLK;
;     ...
;   A_WAITBAR(6);
; __global__ void __launch_bounds__(NWAVES * 64, 2) mega_fwd(Args args) {
;     ...
;                 { const att::hbf* Qp = (const att::hbf*)(PROJ + qrow * LDP + C_DQ + (2 * h + 1) * 128);
;                   const att::hbf* Kp = (const att::hbf*)(PROJ + krow * LDP + C_DK + (2 * h + 1) * 128);
;                   att::attn256_unit<1>(Qp, Kp, Vp, SEQ, (char*)lds, CUR_TID(), stash, XB + qrow * DM + 2048 + h * 256, lam, subln_w); }
	global_store_dwordx4 v[16:17], v[0:3], off offset:1024
	v_pk_mul_f32 v[98:99], v[110:111], v[128:129]
	global_store_dwordx4 v[80:81], v[64:67], off offset:2048
	v_pk_mul_f32 v[0:1], v[8:9], v[136:137]
	v_pk_mul_f32 v[2:3], v[10:11], v[134:135]
	v_pk_mul_f32 v[64:65], v[76:77], v[130:131]
	v_pk_mul_f32 v[66:67], v[78:79], v[128:129]
	global_store_dwordx4 v[48:49], v[32:35], off offset:2048
	global_store_dwordx4 v[16:17], v[0:3], off offset:2048
	global_store_dwordx4 v[112:113], v[96:99], off offset:3072
	v_pk_mul_f32 v[32:33], v[44:45], v[130:131]
	v_pk_mul_f32 v[34:35], v[46:47], v[128:129]
	v_pk_mul_f32 v[0:1], v[12:13], v[130:131]
	v_pk_mul_f32 v[2:3], v[14:15], v[128:129]
	global_store_dwordx4 v[80:81], v[64:67], off offset:3072
	global_store_dwordx4 v[48:49], v[32:35], off offset:3072
	global_store_dwordx4 v[16:17], v[0:3], off offset:3072
	s_or_b32 s0, s4, 0x100
	s_add_u32 s24, s5, s0
	v_mbcnt_lo_u32_b32 v0, -1, 0
	v_mbcnt_hi_u32_b32 v0, -1, v0
	s_addc_u32 s25, s6, 0
	v_add_u32_e32 v0, s59, v0
	v_mov_b64_e32 v[2:3], s[50:51]
	v_readfirstlane_b32 s6, v0
	s_ashr_i32 s38, s6, 6
	v_and_b32_e32 v250, 31, v0
	s_lshl_b32 s28, s38, 5
	v_bfe_u32 v213, v0, 5, 1
	v_or_b32_e32 v1, s28, v250
	v_mad_i64_i32 v[2:3], s[8:9], v1, s68, v[2:3]
	v_lshlrev_b32_e32 v198, 4, v213
	v_mov_b32_e32 v199, v193
	v_lshl_add_u64 v[2:3], v[2:3], 0, v[198:199]
	v_lshl_add_u64 v[2:3], v[2:3], 0, s[0:1]
	global_load_dwordx4 v[160:163], v[2:3], off offset:224
	global_load_dwordx4 v[164:167], v[2:3], off offset:192
	global_load_dwordx4 v[168:171], v[2:3], off offset:160
	global_load_dwordx4 v[172:175], v[2:3], off offset:128
	global_load_dwordx4 v[176:179], v[2:3], off offset:96
	global_load_dwordx4 v[180:183], v[2:3], off offset:64
	global_load_dwordx4 v[184:187], v[2:3], off offset:32
	global_load_dwordx4 v[188:191], v[2:3], off
	s_lshl_b32 s0, s38, 3
	v_bfe_u32 v1, v0, 4, 2
	v_and_b32_e32 v2, 15, v0
	s_and_b32 s5, s38, 1
	v_or_b32_e32 v3, s0, v1
	v_lshlrev_b32_e32 v4, 1, v1
	v_bitop3_b32 v4, v4, v2, s5 bitop3:0x36
	v_mul_lo_u32 v3, v3, s68
	v_or_b32_e32 v1, 4, v1
	v_lshl_or_b32 v192, v4, 4, v3
	v_or_b32_e32 v3, s0, v1
	v_lshlrev_b32_e32 v1, 1, v1
	v_bitop3_b32 v1, v1, v2, s5 bitop3:0x36
	v_mul_lo_u32 v2, v3, s68
	v_lshl_add_u32 v202, v1, 4, v2
	v_bfe_u32 v1, v0, 2, 3
	v_lshrrev_b32_e32 v2, 1, v0
	v_lshl_or_b32 v1, s38, 4, v1
	v_and_b32_e32 v2, 8, v2
	v_lshlrev_b32_e32 v199, 4, v0
	v_and_b32_e32 v1, 55, v1
	v_and_b32_e32 v2, 48, v199
	s_and_b32 s0, s6, 0xffffff00
	v_lshlrev_b32_e32 v3, 6, v213
	s_lshl_b32 s5, s6, 6
	s_lshl_b32 s7, s38, 12
	v_or3_b32 v2, s0, v2, v3
	s_lshl_b32 s0, s38, 11
	s_and_b32 s5, s5, 0xffffc000
	s_and_b32 s7, s7, 0x3000
	s_cmp_lg_u32 0, -1
	v_or_b32_e32 v3, 0x80, v2
	v_mov_b32_e32 v4, 0x30000
	s_cselect_b32 s8, 0, 0
	v_mad_u32_u24 v204, v1, s68, v2
	v_mad_u32_u24 v206, v1, s68, v3
	v_mad_u32_u24 v1, v1, s68, v4
	s_add_i32 s5, s8, s5
	v_add_u32_e32 v208, v1, v2
	v_add_u32_e32 v210, v1, v3
	s_add_i32 s0, s0, s8
	s_add_i32 s5, s5, s7
	s_waitcnt vmcnt(0)
	v_lshl_add_u64 v[2:3], s[24:25], 0, v[192:193]
	s_mov_b32 s7, m0
	s_mov_b32 m0, s0
	s_nop 0
	global_load_lds_dwordx4 v[2:3], off
	s_mov_b32 m0, s7
	v_mov_b32_e32 v203, v193
	v_lshl_add_u64 v[2:3], s[24:25], 0, v[202:203]
	s_add_i32 s7, s0, 0x400
	s_mov_b32 s8, m0
	s_mov_b32 m0, s7
	s_nop 0
	global_load_lds_dwordx4 v[2:3], off
	s_mov_b32 m0, s8
	v_mov_b32_e32 v205, v193
	s_add_i32 s5, s5, 0xc000
	v_lshl_add_u64 v[2:3], s[94:95], 0, v[204:205]
	s_mov_b32 s7, m0
	s_mov_b32 m0, s5
	s_nop 0
	global_load_lds_dwordx4 v[2:3], off
	s_mov_b32 m0, s7
	v_mov_b32_e32 v207, v193
	v_lshl_add_u64 v[2:3], s[94:95], 0, v[206:207]
	s_add_i32 s7, s5, 0x400
	s_mov_b32 s8, m0
	s_mov_b32 m0, s7
	s_nop 0
	global_load_lds_dwordx4 v[2:3], off
	s_mov_b32 m0, s8
	v_mov_b32_e32 v209, v193
	v_lshl_add_u64 v[2:3], s[94:95], 0, v[208:209]
	s_add_i32 s7, s5, 0x800
	s_mov_b32 s8, m0
	s_mov_b32 m0, s7
	s_nop 0
	global_load_lds_dwordx4 v[2:3], off
	s_mov_b32 m0, s8
	v_mov_b32_e32 v211, v193
	v_lshl_add_u64 v[2:3], s[94:95], 0, v[210:211]
	s_add_i32 s7, s5, 0xc00
	s_mov_b32 s8, m0
	s_mov_b32 m0, s7
	s_nop 0
	global_load_lds_dwordx4 v[2:3], off
	s_mov_b32 m0, s8
	s_add_u32 s8, s24, 0x180000
	s_addc_u32 s9, s25, 0
	s_add_i32 s7, s0, 0x4000
	v_lshl_add_u64 v[2:3], s[8:9], 0, v[192:193]
	s_mov_b32 s10, m0
	s_mov_b32 m0, s7
	s_nop 0
	global_load_lds_dwordx4 v[2:3], off
	s_mov_b32 m0, s10
	v_lshl_add_u64 v[2:3], s[8:9], 0, v[202:203]
	s_add_i32 s7, s0, 0x4400
	s_mov_b32 s8, m0
	s_mov_b32 m0, s7
	s_nop 0
	global_load_lds_dwordx4 v[2:3], off
	s_mov_b32 m0, s8
	s_add_i32 s7, s5, 0x8000
	v_lshl_add_u64 v[2:3], s[52:53], 0, v[204:205]
	s_mov_b32 s8, m0
	s_mov_b32 m0, s7
	s_nop 0
	global_load_lds_dwordx4 v[2:3], off
	s_mov_b32 m0, s8
	v_lshl_add_u64 v[2:3], s[52:53], 0, v[206:207]
	s_add_i32 s7, s5, 0x8400
	s_mov_b32 s8, m0
	s_mov_b32 m0, s7
	s_nop 0
	global_load_lds_dwordx4 v[2:3], off
	s_mov_b32 m0, s8
	v_lshl_add_u64 v[2:3], s[52:53], 0, v[208:209]
	s_add_i32 s7, s5, 0x8800
	s_mov_b32 s8, m0
	s_mov_b32 m0, s7
	s_nop 0
	global_load_lds_dwordx4 v[2:3], off
	s_mov_b32 m0, s8
	v_lshl_add_u64 v[2:3], s[52:53], 0, v[210:211]
	s_add_i32 s7, s5, 0x8c00
	s_mov_b32 s8, m0
	s_mov_b32 m0, s7
	s_nop 0
	global_load_lds_dwordx4 v[2:3], off
	s_mov_b32 m0, s8
	s_waitcnt vmcnt(4) lgkmcnt(0)
	s_barrier
	s_cmp_lt_i32 s38, 4
	s_cbranch_scc1 .LBB0_380
	s_barrier
; __device__ __forceinline__ int v_rd_base(int lane) { return ((lane & 3) << 3) | (((lane >> 2) & 3) << 6) | (((lane >> 4) & 1) << 5) | (((lane >> 5) & 1) << 8); }
; #define KRD(A, B, d0) do { const int ad_ = (kc ^ ((d0) << 5)) + kbt; A = lds_rd128<0>(ad_); B = lds_rd128<8192>(ad_); } while (0)
; #define A_WAITBAR(N) asm volatile("s_waitcnt vmcnt(" #N ") lgkmcnt(0) ; A256BAR\n\ts_barrier" ::: "memory")
; __device__ __forceinline__ void qkt_pipe(f32x16& p0, f32x16& p1, int kbt, int kc, const bf16x8* qr, const f32x16& z) {
;     ...
;   KRD(a0, b0, 0); KRD(a1, b1, 1); KRD(a2, b2, 2); KRD(a3, b3, 3);
; template <int mode> ...
;     ...
;   float m_reg = 0.f, l_reg = 0; f32x16 o[8] = {};
;   const int vb0 = (int)(lds0 + A_LDS_V) + v_rd_base(lane);
;   const int kb0 = (int)(lds0 + A_LDS_K) + r32 * 256, kc = (hi << 4) ^ ((((r32 & 7) << 1) | ((r32 >> 3) & 1)) << 4);
;   const int NT = seq / KVBLK;
;     ...
;   A_WAITBAR(6);
;   if (wid >= 4) asm volatile("s_barrier" ::: "memory");
;   int s0 = 0, s1 = 1, s2 = 2;
.LBB0_380:
	s_and_b32 s6, s6, 0x3fffffc0
	s_lshl_b32 s6, s6, 2
	s_add_i32 s6, s6, 0
	v_lshlrev_b32_e32 v5, 1, v0
	v_and_b32_e32 v1, 63, v0
	s_add_i32 s6, s6, 0x24000
	v_and_b32_e32 v5, 14, v5
	v_bfe_u32 v0, v0, 3, 1
	v_lshlrev_b32_e32 v2, 3, v1
	s_cmp_lg_u32 0, -1
	v_bitop3_b32 v0, v5, v213, v0 bitop3:0x36
	v_lshlrev_b32_e32 v200, 4, v1
	v_lshlrev_b32_e32 v4, 1, v1
	s_cselect_b32 s9, 0, 0
	v_lshlrev_b32_e32 v225, 4, v0
	v_and_b32_e32 v0, 0x118, v2
	v_and_b32_e32 v3, 0xc0, v200
	v_lshl_add_u32 v201, v250, 8, s9
	v_and_or_b32 v0, v4, 32, v0
	s_add_i32 s9, s9, 0xc000
	v_mov_b32_e32 v16, v193
	v_mov_b32_e32 v17, v193
	v_mov_b32_e32 v30, v193
	v_mov_b32_e32 v31, v193
	v_cmp_gt_u32_e64 s[40:41], 32, v1
	v_add3_u32 v226, v3, s9, v0
	v_mov_b32_e32 v18, v193
	v_mov_b32_e32 v19, v193
	v_mov_b32_e32 v20, v193
	v_mov_b32_e32 v21, v193
	v_mov_b32_e32 v22, v193
	v_mov_b32_e32 v23, v193
	v_mov_b32_e32 v24, v193
	v_mov_b32_e32 v25, v193
	v_mov_b32_e32 v26, v193
	v_mov_b32_e32 v27, v193
	v_mov_b32_e32 v28, v193
	v_mov_b32_e32 v29, v193
	v_mov_b64_e32 v[46:47], v[30:31]
	v_mov_b64_e32 v[110:111], v[30:31]
	v_mov_b64_e32 v[126:127], v[30:31]
	v_mov_b64_e32 v[78:79], v[30:31]
	v_mov_b64_e32 v[62:63], v[30:31]
	v_mov_b64_e32 v[0:1], v[16:17]
	v_mov_b64_e32 v[94:95], v[30:31]
	s_mov_b32 s7, 2
	s_mov_b32 s8, 1
	s_mov_b32 s11, 0
	v_lshl_add_u32 v224, v250, 2, s6
	v_mov_b32_e32 v227, 0
	v_mov_b64_e32 v[44:45], v[28:29]
	v_mov_b64_e32 v[42:43], v[26:27]
	v_mov_b64_e32 v[40:41], v[24:25]
	v_mov_b64_e32 v[38:39], v[22:23]
	v_mov_b64_e32 v[36:37], v[20:21]
	v_mov_b64_e32 v[34:35], v[18:19]
	v_mov_b64_e32 v[32:33], v[16:17]
	v_mov_b64_e32 v[108:109], v[28:29]
	v_mov_b64_e32 v[106:107], v[26:27]
	v_mov_b64_e32 v[104:105], v[24:25]
	v_mov_b64_e32 v[102:103], v[22:23]
	v_mov_b64_e32 v[100:101], v[20:21]
	v_mov_b64_e32 v[98:99], v[18:19]
	v_mov_b64_e32 v[96:97], v[16:17]
	v_mov_b64_e32 v[124:125], v[28:29]
	v_mov_b64_e32 v[122:123], v[26:27]
	v_mov_b64_e32 v[120:121], v[24:25]
	v_mov_b64_e32 v[118:119], v[22:23]
	v_mov_b64_e32 v[116:117], v[20:21]
	v_mov_b64_e32 v[114:115], v[18:19]
	v_mov_b64_e32 v[112:113], v[16:17]
	v_mov_b64_e32 v[76:77], v[28:29]
	v_mov_b64_e32 v[74:75], v[26:27]
	v_mov_b64_e32 v[72:73], v[24:25]
	v_mov_b64_e32 v[70:71], v[22:23]
	v_mov_b64_e32 v[68:69], v[20:21]
	v_mov_b64_e32 v[66:67], v[18:19]
	v_mov_b64_e32 v[64:65], v[16:17]
	v_mov_b64_e32 v[60:61], v[28:29]
	v_mov_b64_e32 v[58:59], v[26:27]
	v_mov_b64_e32 v[56:57], v[24:25]
	v_mov_b64_e32 v[54:55], v[22:23]
	v_mov_b64_e32 v[52:53], v[20:21]
	v_mov_b64_e32 v[50:51], v[18:19]
	v_mov_b64_e32 v[48:49], v[16:17]
	v_mov_b64_e32 v[2:3], v[18:19]
	v_mov_b64_e32 v[4:5], v[20:21]
	v_mov_b64_e32 v[6:7], v[22:23]
	v_mov_b64_e32 v[8:9], v[24:25]
	v_mov_b64_e32 v[10:11], v[26:27]
	v_mov_b64_e32 v[12:13], v[28:29]
	v_mov_b64_e32 v[14:15], v[30:31]
	v_mov_b64_e32 v[92:93], v[28:29]
	v_mov_b64_e32 v[90:91], v[26:27]
	v_mov_b64_e32 v[88:89], v[24:25]
	v_mov_b64_e32 v[86:87], v[22:23]
	v_mov_b64_e32 v[84:85], v[20:21]
	v_mov_b64_e32 v[82:83], v[18:19]
	v_mov_b64_e32 v[80:81], v[16:17]
	s_mov_b32 s9, 0
	v_mov_b32_e32 v228, 0
	v_lshl_add_u32 v212, s11, 14, v201
	v_add_u32_e32 v144, v212, v225
	ds_read_b128 v[194:197], v144 offset:0
	ds_read_b128 v[214:217], v144 offset:0x2000
	v_xor_b32_e32 v144, 32, v225
	v_add_u32_e32 v144, v212, v144
	ds_read_b128 v[230:233], v144 offset:0
	ds_read_b128 v[234:237], v144 offset:0x2000
	v_xor_b32_e32 v144, 64, v225
	v_add_u32_e32 v144, v212, v144
	ds_read_b128 v[238:241], v144 offset:0
	ds_read_b128 v[242:245], v144 offset:0x2000
	v_xor_b32_e32 v144, 0x60, v225
	v_add_u32_e32 v144, v212, v144
	ds_read_b128 v[246:249], v144 offset:0
	ds_read_b128 v[220:223], v144 offset:0x2000
.LBB0_381:
	s_mov_b32 s10, s11
	s_setprio 2
	s_add_i32 s11, s9, 2
	s_cmp_lt_u32 s11, s74
	s_cselect_b64 s[52:53], -1, 0
	s_cmp_ge_u32 s11, s74
	s_cselect_b64 s[50:51], -1, 0
	s_and_b64 vcc, exec, s[50:51]
	v_xor_b32_e32 v128, 0x80000000, v227
	v_mov_b32_e32 v129, v128
	v_mov_b32_e32 v130, v128
	v_mov_b32_e32 v131, v128
	v_mov_b32_e32 v132, v128
	v_mov_b32_e32 v133, v128
	v_mov_b32_e32 v134, v128
	v_mov_b32_e32 v135, v128
	v_mov_b32_e32 v136, v128
	v_mov_b32_e32 v137, v128
	v_mov_b32_e32 v138, v128
	v_mov_b32_e32 v139, v128
	v_mov_b32_e32 v140, v128
	v_mov_b32_e32 v141, v128
	v_mov_b32_e32 v142, v128
	v_mov_b32_e32 v143, v128
	s_waitcnt lgkmcnt(6)
	s_nop 1
	v_mfma_f32_32x32x16_bf16 v[144:159], v[194:197], v[188:191], v[128:143]
	v_mfma_f32_32x32x16_bf16 v[128:143], v[214:217], v[188:191], v[128:143]
	v_xor_b32_e32 v194, 0x80, v225
	v_add_u32_e32 v229, v212, v194
	ds_read_b128 v[194:197], v229 offset:0
	ds_read_b128 v[214:217], v229 offset:0x2000
	s_cbranch_vccnz .Lq1_nodma
	s_add_u32 s24, s60, 0xfffff100
	s_addc_u32 s25, s61, -1
	s_lshl_b32 s11, s7, 14
	s_add_i32 s11, s11, s0
	s_mov_b32 s12, m0
	s_mov_b32 m0, s11
	s_nop 0
	global_load_lds_dwordx4 v192, s[24:25]
	s_addk_i32 s11, 0x400
	s_mov_b32 m0, s11
	s_nop 0
	global_load_lds_dwordx4 v202, s[24:25]
	s_mov_b32 m0, s12

; #define SBAR() __builtin_amdgcn_sched_barrier(0)
; #define KRD(A, B, d0) do { const int ad_ = (kc ^ ((d0) << 5)) + kbt; A = lds_rd128<0>(ad_); B = lds_rd128<8192>(ad_); } while (0)
; #define VF_WAIT(N) do { asm volatile("s_waitcnt lgkmcnt(" #N ")" ::: "memory"); SBAR(); } while (0)
; __device__ __forceinline__ float softmax_rel(f32x16& p0, f32x16& p1, bool first, float& m_reg, float& l_reg, bf16x8& pa0, bf16x8& pa1, bf16x8& pa2, bf16x8& pa3) {
;     ...
;   l_reg = l_reg * alpha + ps;
;   PK4(p0, 0, pa0); PK4(p0, 8, pa1); PK4(p1, 0, pa2); PK4(p1, 8, pa3);
;   return alpha;
; }
; template <int OFF> __device__ __forceinline__ bf16x8 lds_rd128(int addr) { bf16x8 r; asm volatile("ds_read_b128 %0, %1 offset:%2" : "=&v"(r) : "v"(addr), "i"(OFF) : "memory"); return r; }
; __device__ __forceinline__ void qkt_pipe(f32x16& p0, f32x16& p1, int kbt, int kc, const bf16x8* qr, const f32x16& z) {
;   bf16x8 a0, b0, a1, b1, a2, b2, a3, b3;
;     ...
;   KRD(a0, b0, 0); KRD(a1, b1, 1); KRD(a2, b2, 2); KRD(a3, b3, 3);
; __device__ __forceinline__ void pv8(f32x16* o, int vb, bf16x8 pa0, bf16x8 pa1, bf16x8 pa2, bf16x8 pa3) {
;     ...
;   vf_read<1>(fb, vb);  VF_WAIT(8); vf_mma(o[0], fa, pa0, pa1, pa2, pa3); SBAR();
;   vf_read<2>(fa, vb);  VF_WAIT(8); vf_mma(o[1], fb, pa0, pa1, pa2, pa3); SBAR();
;   vf_read<3>(fb, vb);  VF_WAIT(8); vf_mma(o[2], fa, pa0, pa1, pa2, pa3); SBAR();
;   vf_read<0>(fa, vb2); VF_WAIT(8); vf_mma(o[3], fb, pa0, pa1, pa2, pa3); SBAR();
;   vf_read<1>(fb, vb2); VF_WAIT(8); vf_mma(o[4], fa, pa0, pa1, pa2, pa3); SBAR();
;   vf_read<2>(fa, vb2); VF_WAIT(8); vf_mma(o[5], fb, pa0, pa1, pa2, pa3); SBAR();
;   vf_read<3>(fb, vb2); VF_WAIT(8); vf_mma(o[6], fa, pa0, pa1, pa2, pa3); SBAR();
;   VF_WAIT(0); vf_mma(o[7], fb, pa0, pa1, pa2, pa3);
; }
.Lp1_nodma:
	s_waitcnt lgkmcnt(8)
	v_mfma_f32_32x32x16_bf16 v[32:47], v[128:131], v[194:197], v[32:47]
	v_mfma_f32_32x32x16_bf16 v[32:47], v[132:135], v[214:217], v[32:47]
	v_mfma_f32_32x32x16_bf16 v[32:47], v[136:139], v[220:223], v[32:47]
	v_mfma_f32_32x32x16_bf16 v[32:47], v[140:143], v[232:235], v[32:47]
	ds_read_b64_tr_b16 v[194:195], v231 offset:0x600
	ds_read_b64_tr_b16 v[196:197], v231 offset:0xe00
	ds_read_b64_tr_b16 v[214:215], v231 offset:0x1600
	ds_read_b64_tr_b16 v[216:217], v231 offset:0x1e00
	ds_read_b64_tr_b16 v[220:221], v231 offset:0x2600
	ds_read_b64_tr_b16 v[222:223], v231 offset:0x2e00
	ds_read_b64_tr_b16 v[232:233], v231 offset:0x3600
	ds_read_b64_tr_b16 v[234:235], v231 offset:0x3e00
	s_waitcnt lgkmcnt(8)
	v_mfma_f32_32x32x16_bf16 v[96:111], v[128:131], v[144:147], v[96:111]
	v_mfma_f32_32x32x16_bf16 v[96:111], v[132:135], v[148:151], v[96:111]
	v_mfma_f32_32x32x16_bf16 v[96:111], v[136:139], v[152:155], v[96:111]
	v_mfma_f32_32x32x16_bf16 v[96:111], v[140:143], v[156:159], v[96:111]
	ds_read_b64_tr_b16 v[144:145], v236 offset:0
	ds_read_b64_tr_b16 v[146:147], v236 offset:0x800
	ds_read_b64_tr_b16 v[148:149], v236 offset:0x1000
	ds_read_b64_tr_b16 v[150:151], v236 offset:0x1800
	ds_read_b64_tr_b16 v[152:153], v236 offset:0x2000
	ds_read_b64_tr_b16 v[154:155], v236 offset:0x2800
	ds_read_b64_tr_b16 v[156:157], v236 offset:0x3000
	ds_read_b64_tr_b16 v[158:159], v236 offset:0x3800
	s_waitcnt lgkmcnt(8)
	v_mfma_f32_32x32x16_bf16 v[112:127], v[128:131], v[194:197], v[112:127]
	v_mfma_f32_32x32x16_bf16 v[112:127], v[132:135], v[214:217], v[112:127]
	v_mfma_f32_32x32x16_bf16 v[112:127], v[136:139], v[220:223], v[112:127]
	v_mfma_f32_32x32x16_bf16 v[112:127], v[140:143], v[232:235], v[112:127]
	ds_read_b64_tr_b16 v[194:195], v236 offset:0x200
	ds_read_b64_tr_b16 v[196:197], v236 offset:0xa00
	ds_read_b64_tr_b16 v[214:215], v236 offset:0x1200
	ds_read_b64_tr_b16 v[216:217], v236 offset:0x1a00
	ds_read_b64_tr_b16 v[220:221], v236 offset:0x2200
	ds_read_b64_tr_b16 v[222:223], v236 offset:0x2a00
	ds_read_b64_tr_b16 v[232:233], v236 offset:0x3200
	ds_read_b64_tr_b16 v[234:235], v236 offset:0x3a00
	s_waitcnt lgkmcnt(8)
	v_mfma_f32_32x32x16_bf16 v[64:79], v[128:131], v[144:147], v[64:79]
	v_mfma_f32_32x32x16_bf16 v[64:79], v[132:135], v[148:151], v[64:79]
	v_mfma_f32_32x32x16_bf16 v[64:79], v[136:139], v[152:155], v[64:79]
	v_mfma_f32_32x32x16_bf16 v[64:79], v[140:143], v[156:159], v[64:79]
	ds_read_b64_tr_b16 v[144:145], v236 offset:0x400
	ds_read_b64_tr_b16 v[146:147], v236 offset:0xc00
	ds_read_b64_tr_b16 v[148:149], v236 offset:0x1400
	ds_read_b64_tr_b16 v[150:151], v236 offset:0x1c00
	ds_read_b64_tr_b16 v[152:153], v236 offset:0x2400
	ds_read_b64_tr_b16 v[154:155], v236 offset:0x2c00
	ds_read_b64_tr_b16 v[156:157], v236 offset:0x3400
	ds_read_b64_tr_b16 v[158:159], v236 offset:0x3c00
	s_waitcnt lgkmcnt(8)
	v_mfma_f32_32x32x16_bf16 v[48:63], v[128:131], v[194:197], v[48:63]
	v_mfma_f32_32x32x16_bf16 v[48:63], v[132:135], v[214:217], v[48:63]
	v_mfma_f32_32x32x16_bf16 v[48:63], v[136:139], v[220:223], v[48:63]
	v_mfma_f32_32x32x16_bf16 v[48:63], v[140:143], v[232:235], v[48:63]
	ds_read_b64_tr_b16 v[194:195], v236 offset:0x600
	ds_read_b64_tr_b16 v[196:197], v236 offset:0xe00
	ds_read_b64_tr_b16 v[214:215], v236 offset:0x1600
	ds_read_b64_tr_b16 v[216:217], v236 offset:0x1e00
	ds_read_b64_tr_b16 v[220:221], v236 offset:0x2600
	ds_read_b64_tr_b16 v[222:223], v236 offset:0x2e00
	ds_read_b64_tr_b16 v[232:233], v236 offset:0x3600
	ds_read_b64_tr_b16 v[234:235], v236 offset:0x3e00
	s_waitcnt lgkmcnt(8)
	v_mfma_f32_32x32x16_bf16 v[0:15], v[128:131], v[144:147], v[0:15]
	v_mfma_f32_32x32x16_bf16 v[0:15], v[132:135], v[148:151], v[0:15]
	v_mfma_f32_32x32x16_bf16 v[0:15], v[136:139], v[152:155], v[0:15]
	v_mfma_f32_32x32x16_bf16 v[0:15], v[140:143], v[156:159], v[0:15]
	s_waitcnt lgkmcnt(0)
	v_mfma_f32_32x32x16_bf16 v[80:95], v[128:131], v[194:197], v[80:95]
	s_and_b64 vcc, exec, s[50:51]
	v_mfma_f32_32x32x16_bf16 v[80:95], v[132:135], v[214:217], v[80:95]
	v_mfma_f32_32x32x16_bf16 v[80:95], v[136:139], v[220:223], v[80:95]
	v_mfma_f32_32x32x16_bf16 v[80:95], v[140:143], v[232:235], v[80:95]
	v_add_f32_e32 v128, v212, v230
	v_fmac_f32_e32 v128, v228, v229
	s_add_i32 s12, s9, 1
	s_cmp_ge_u32 s12, s74
	s_cbranch_scc1 .Lm1_nopre
	v_lshl_add_u32 v212, s8, 14, v201
	v_add_u32_e32 v144, v212, v225
	ds_read_b128 v[194:197], v144 offset:0
	ds_read_b128 v[214:217], v144 offset:0x2000
	v_xor_b32_e32 v144, 32, v225
	v_add_u32_e32 v144, v212, v144
	ds_read_b128 v[230:233], v144 offset:0
	ds_read_b128 v[234:237], v144 offset:0x2000
	v_xor_b32_e32 v144, 64, v225
	v_add_u32_e32 v144, v212, v144
	ds_read_b128 v[238:241], v144 offset:0
	ds_read_b128 v[242:245], v144 offset:0x2000
	v_xor_b32_e32 v144, 0x60, v225
	v_add_u32_e32 v144, v212, v144
	ds_read_b128 v[246:249], v144 offset:0
	ds_read_b128 v[220:223], v144 offset:0x2000

; #define A_WAITBAR(N) asm volatile("s_waitcnt vmcnt(" #N ") lgkmcnt(0) ; A256BAR\n\ts_barrier" ::: "memory")
; #define DMA_K(t, sl) do { const char* b_ = Kb + (size_t)(t) * TSTRIDE; const unsigned d_ = RFL(kdst + (sl) * 16384); glds16(b_ + koff[0], d_); glds16(b_ + koff[1], d_ + 1024); } while (0)
; #define DMA_V(t, sl) do { const char* b_ = Vb + (size_t)(t) * TSTRIDE; const unsigned d_ = RFL(vdst + (sl) * 32768); glds16(b_ + voff[0], d_); glds16(b_ + voff[1], d_ + 1024); glds16(b_ + voff[2], d_ + 2048); glds16(b_ + voff[3], d_ + 3072); } while (0)
; #define RESC(a) do { if (__any((a) < 1.f)) { if (hi == 0) al_l[r32] = (a); asm volatile("s_waitcnt lgkmcnt(0)" ::: "memory"); \
;     _Pragma("unroll") for (int d = 0; d < 8; ++d) _Pragma("unroll") for (int r = 0; r < 16; ++r) o[d][r] *= al_l[crow(r, hi)]; } } while (0)
; template <int mode> ...
;     ...
;   for (int j = 0; j < NT; ++j) {
;     const bool more = j + 2 < NT;
;     if (more) DMA_K(j + 2, s2);
;     f32x16 p0, p1; bf16x8 pa0, pa1, pa2, pa3;
;     __builtin_amdgcn_s_setprio(2);
;     { f32x16 negm;
; #pragma unroll
;       for (int r = 0; r < 16; ++r) negm[r] = -m_reg;
;       qkt_pipe(p0, p1, kb0 + s0 * 16384, kc, qr, negm); }
;     const float alpha = softmax_rel(p0, p1, j == 0, m_reg, l_reg, pa0, pa1, pa2, pa3);
;     RESC(alpha);
;     __builtin_amdgcn_s_setprio(0);
;     if (more) A_WAITBAR(6); else A_WAITBAR(0);
;     if (more) DMA_V(j + 2, s2);
;     pv8(o, vb0 + s0 * 32768, pa0, pa1, pa2, pa3);
;     if (more) A_WAITBAR(6); else A_WAITBAR(0);
;     { const int t_ = s0; s0 = s1; s1 = s2; s2 = t_; }
.LBB0_400:
	s_add_i32 s9, s9, 1
	s_add_u32 s60, s60, 0x180000
	s_addc_u32 s61, s61, 0
	s_cmp_eq_u32 s74, s9
	s_cbranch_scc1 .LBB0_407
	s_mov_b32 s11, s8
	s_mov_b32 s8, s7
	s_mov_b32 s7, s10
	v_mov_b32_e32 v228, v128
	s_branch .LBB0_381
